# static s_setprio 1 for waves 4-7 (younger half) during the attention phase, reset at phase end; on top of shw_gemm DPP reduction
# baseline (speedup 1.0000x reference)
.LBB0_938:
	s_cmp_lt_i32 s92, 13
	s_cselect_b64 s[38:39], -1, 0
	s_cmp_gt_i32 s93, 12
	s_cselect_b64 s[0:1], -1, 0
	s_and_b64 s[0:1], s[38:39], s[0:1]
	s_andn2_b64 vcc, exec, s[0:1]
	s_cbranch_vccnz .LBB0_1002
	s_cmpk_gt_i32 s2, 0x7ff
	v_readfirstlane_b32 s0, v166
	s_cbranch_scc1 .LBB0_1001
	s_add_u32 s3, s90, 0x1e600000
	v_lshrrev_b32_e32 v1, 4, v166
	v_lshlrev_b32_e32 v2, 4, v166
	v_bfe_u32 v7, v166, 5, 1
	s_addc_u32 s33, s91, 0
	v_mul_u32_u24_e32 v1, 0x110, v1
	v_and_b32_e32 v6, 0xf0, v2
	v_mov_b32_e32 v131, 0
	v_lshlrev_b32_e32 v130, 4, v7
	s_add_u32 s58, s90, 0x33600000
	v_lshl_add_u64 v[4:5], s[90:91], 0, v[130:131]
	s_mov_b64 s[4:5], 0x2a600000
	v_add3_u32 v146, v1, v6, 0
	v_lshrrev_b32_e32 v1, 2, v166
	v_lshlrev_b32_e32 v147, 2, v7
	s_addc_u32 s59, s91, 0
	s_movk_i32 s60, 0x110
	v_lshl_add_u64 v[132:133], v[4:5], 0, s[4:5]
	v_lshlrev_b32_e32 v4, 3, v166
	v_and_or_b32 v1, v1, 3, v147
	v_lshlrev_b32_e32 v6, 1, v166
	s_add_u32 s52, s90, 0x32600000
	v_mad_u32_u24 v1, v1, s60, 0
	v_and_b32_e32 v6, 32, v6
	v_and_b32_e32 v8, 24, v4
	s_addc_u32 s53, s91, 0
	v_and_b32_e32 v135, 31, v166
	v_add3_u32 v148, v1, v6, v8
	v_lshrrev_b32_e32 v1, 3, v166
	s_lshr_b32 s1, s0, 6
	s_bfe_u32 s63, s0, 0x20006
	s_lshr_b32 s0, s0, 8
	v_and_b32_e32 v151, 7, v166
	v_mul_u32_u24_e32 v6, 33, v1
	s_add_i32 s61, 0, 0x11000
	v_lshl_or_b32 v157, s0, 5, v135
	s_lshl_b32 s64, s0, 2
	s_lshl_b32 s0, s1, 13
	v_and_b32_e32 v3, 63, v166
	v_lshlrev_b32_e32 v5, 2, v166
	v_lshlrev_b32_e32 v6, 2, v6
	v_lshlrev_b32_e32 v8, 4, v151
	s_add_i32 s62, 0, 0x19400
	s_add_i32 s0, s0, s61
	v_add3_u32 v153, s61, v6, v8
	v_add3_u32 v154, s62, v6, v8
	v_lshrrev_b32_e32 v6, 6, v166
	v_lshlrev_b32_e32 v8, 2, v1
	v_lshl_add_u32 v158, v3, 2, s0
	v_add_u32_e32 v3, 0, v5
	v_and_b32_e32 v6, 12, v6
	v_add_u32_e32 v160, 0x21900, v3
	v_add_u32_e32 v3, 0, v8
	v_lshl_add_u32 v9, s63, 6, v157
	v_lshlrev_b32_e32 v10, 2, v157
	v_add_u32_e32 v161, 0x21800, v3
	v_add_u32_e32 v3, 0, v6
	v_lshlrev_b32_e32 v2, 3, v7
	v_add_u32_e32 v149, 0, v130
	v_lshlrev_b32_e32 v152, 2, v151
	v_lshl_add_u32 v9, v9, 5, v9
	v_add_u32_e32 v162, 0x21900, v3
	v_add_u32_e32 v3, 0, v10
	s_mov_b32 s55, 0
	v_mad_u32_u24 v150, v135, s60, v149
	v_cmp_eq_u32_e64 s[6:7], 0, v151
	v_cmp_ne_u32_e64 s[8:9], 0, v151
	v_add_u32_e32 v155, -4, v154
	v_or_b32_e32 v156, 1, v152
	v_or_b32_e32 v1, 3, v152
	v_or_b32_e32 v134, 2, v152
	v_add_lshl_u32 v159, v9, v7, 2
	s_movk_i32 s65, 0x2000
	s_mov_b32 s66, 0xf149f2ca
	s_mov_b32 s67, 0xf0c9f2ca
	s_movk_i32 s68, 0xc0
	v_add_u32_e32 v163, 0x21800, v3
	v_lshlrev_b32_e32 v130, 1, v4
	v_mov_b32_e32 v164, 0xf149f2ca
	v_mov_b32_e32 v165, 0x7149f2ca
	v_lshlrev_b32_e32 v136, 1, v2
	s_cmp_eq_u32 s64, 0
	s_cbranch_scc1 .Lmy_attn_prio_skip
	s_setprio 1
.Lmy_attn_prio_skip:
	s_mov_b32 s69, s2
	s_branch .LBB0_942

.LBB0_1001:
	s_setprio 0
	s_waitcnt lgkmcnt(0)
	s_barrier
